# P0 rmsnorm: pre-norm gain vector loaded once per wave into registers instead of 4 load-wait-store ladders per row (on top of v34)
# speedup vs baseline: 1.0090x; 1.0090x over previous
.LBB0_10:
	s_or_b64 exec, exec, s[4:5]
	s_load_dwordx16 s[8:23], s[0:1], 0x0
	s_lshl_b32 s3, s86, 3
	v_and_b32_e32 v68, 63, v66
	v_mbcnt_lo_u32_b32 v139, -1, 0
	s_waitcnt lgkmcnt(0)
	v_writelane_b32 v252, s8, 14
	s_nop 1
	v_writelane_b32 v252, s9, 15
	v_writelane_b32 v252, s10, 16
	v_writelane_b32 v252, s11, 17
	v_writelane_b32 v252, s12, 18
	v_writelane_b32 v252, s13, 19
	v_writelane_b32 v252, s14, 20
	v_writelane_b32 v252, s15, 21
	v_writelane_b32 v252, s16, 22
	v_writelane_b32 v252, s17, 23
	v_writelane_b32 v252, s18, 24
	v_writelane_b32 v252, s19, 25
	v_writelane_b32 v252, s20, 26
	v_writelane_b32 v252, s21, 27
	v_writelane_b32 v252, s22, 28
	v_writelane_b32 v252, s23, 29
	s_load_dwordx16 s[8:23], s[0:1], 0x40
	s_lshl_b32 s0, s54, 3
	s_waitcnt lgkmcnt(0)
	v_writelane_b32 v252, s8, 30
	s_nop 1
	v_writelane_b32 v252, s9, 31
	v_writelane_b32 v252, s10, 32
	v_writelane_b32 v252, s11, 33
	v_writelane_b32 v252, s12, 34
	v_writelane_b32 v252, s13, 35
	v_writelane_b32 v252, s14, 36
	v_writelane_b32 v252, s15, 37
	v_writelane_b32 v252, s16, 38
	v_writelane_b32 v252, s17, 39
	v_writelane_b32 v252, s18, 40
	v_writelane_b32 v252, s19, 41
	v_writelane_b32 v252, s20, 42
	v_writelane_b32 v252, s21, 43
	v_writelane_b32 v252, s22, 44
	v_writelane_b32 v252, s23, 45
	s_ashr_i32 s18, s2, 6
	s_add_i32 s2, s18, s0
	s_cmpk_gt_i32 s2, 0x407f
	s_cbranch_scc1 .LBB0_25
	v_readlane_b32 s8, v252, 0
	v_mov_b32_e32 v3, 0
	v_lshlrev_b32_e32 v2, 3, v68
	v_readlane_b32 s12, v252, 4
	v_readlane_b32 s13, v252, 5
	v_readlane_b32 s36, v252, 14
	v_readlane_b32 s44, v252, 22
	v_lshl_add_u64 v[70:71], s[12:13], 0, v[2:3]
	v_mbcnt_hi_u32_b32 v2, -1, v139
	v_and_b32_e32 v1, 64, v2
	v_add_u32_e32 v4, 64, v1
	v_xor_b32_e32 v1, 1, v2
	v_cmp_lt_i32_e32 vcc, v1, v4
	v_xor_b32_e32 v5, 2, v2
	v_readlane_b32 s45, v252, 23
	v_cndmask_b32_e32 v1, v2, v1, vcc
	v_cmp_lt_i32_e32 vcc, v5, v4
	v_lshlrev_b32_e32 v1, 2, v1
	s_lshl_b32 s19, s86, 4
	v_cndmask_b32_e32 v5, v2, v5, vcc
	v_lshlrev_b32_e32 v67, 2, v5
	v_xor_b32_e32 v5, 4, v2
	v_cmp_lt_i32_e32 vcc, v5, v4
	s_mul_i32 s20, s86, 24
	v_lshlrev_b32_e32 v77, 4, v68
	v_cndmask_b32_e32 v5, v2, v5, vcc
	v_lshlrev_b32_e32 v69, 2, v5
	v_xor_b32_e32 v5, 8, v2
	v_cmp_lt_i32_e32 vcc, v5, v4
	v_mov_b32_e32 v78, 0x358637bd
	s_mov_b32 s21, 0xf800000
	v_cndmask_b32_e32 v5, v2, v5, vcc
	v_lshlrev_b32_e32 v74, 2, v5
	v_xor_b32_e32 v5, 16, v2
	v_cmp_lt_i32_e32 vcc, v5, v4
	v_mov_b32_e32 v79, 0x260
	s_mov_b32 s0, s2
	v_cndmask_b32_e32 v5, v2, v5, vcc
	v_lshlrev_b32_e32 v75, 2, v5
	v_xor_b32_e32 v5, 32, v2
	v_cmp_lt_i32_e32 vcc, v5, v4
	v_readlane_b32 s9, v252, 1
	v_readlane_b32 s10, v252, 2
	v_cndmask_b32_e32 v2, v2, v5, vcc
	v_lshlrev_b32_e32 v76, 2, v2
	v_lshlrev_b32_e32 v2, 4, v68
	v_lshl_add_u64 v[72:73], s[44:45], 0, v[2:3]
	global_load_dwordx4 v[180:183], v[72:73], off
	global_load_dwordx4 v[184:187], v[72:73], off offset:1024
	global_load_dwordx4 v[188:191], v[72:73], off offset:2048
	global_load_dwordx4 v[192:195], v[72:73], off offset:3072
	v_readlane_b32 s11, v252, 3
	v_readlane_b32 s14, v252, 6
	v_readlane_b32 s15, v252, 7
	v_readlane_b32 s37, v252, 15
	v_readlane_b32 s38, v252, 16
	v_readlane_b32 s39, v252, 17
	v_readlane_b32 s40, v252, 18
	v_readlane_b32 s41, v252, 19
	v_readlane_b32 s42, v252, 20
	v_readlane_b32 s43, v252, 21
	v_readlane_b32 s46, v252, 24
	v_readlane_b32 s47, v252, 25
	v_readlane_b32 s48, v252, 26
	v_readlane_b32 s49, v252, 27
	v_readlane_b32 s50, v252, 28
	v_readlane_b32 s51, v252, 29
	s_branch .LBB0_13

.LBB0_19:
	s_waitcnt vmcnt(3)
	v_mul_f32_e32 v80, v63, v63
	v_mul_f32_e32 v81, v65, v65
	v_fmac_f32_e32 v80, v62, v62
	v_fmac_f32_e32 v81, v64, v64
	v_add_f32_e32 v80, v80, v81
	s_waitcnt vmcnt(2)
	v_mul_f32_e32 v81, v59, v59
	v_mul_f32_e32 v82, v61, v61
	v_fmac_f32_e32 v81, v58, v58
	v_fmac_f32_e32 v82, v60, v60
	v_add_f32_e32 v81, v81, v82
	v_add_f32_e32 v80, v80, v81
	s_waitcnt vmcnt(1)
	v_mul_f32_e32 v81, v55, v55
	v_mul_f32_e32 v82, v57, v57
	v_fmac_f32_e32 v81, v54, v54
	v_fmac_f32_e32 v82, v56, v56
	v_add_f32_e32 v81, v81, v82
	v_add_f32_e32 v84, v80, v81
	s_waitcnt vmcnt(0)
	v_mul_f32_e32 v85, v51, v51
	v_mul_f32_e32 v86, v53, v53
	v_fmac_f32_e32 v85, v50, v50
	v_fmac_f32_e32 v86, v52, v52
	v_add_f32_e32 v85, v85, v86
	v_add_f32_e32 v84, v84, v85
	ds_bpermute_b32 v85, v1, v84
	s_lshl_b64 s[22:23], s[0:1], 11
	s_waitcnt lgkmcnt(0)
	v_add_f32_e32 v84, v84, v85
	ds_bpermute_b32 v85, v67, v84
	s_waitcnt lgkmcnt(0)
	v_add_f32_e32 v84, v84, v85
	ds_bpermute_b32 v85, v69, v84
	s_waitcnt lgkmcnt(0)
	v_add_f32_e32 v84, v84, v85
	ds_bpermute_b32 v85, v74, v84
	s_waitcnt lgkmcnt(0)
	v_add_f32_e32 v84, v84, v85
	ds_bpermute_b32 v85, v75, v84
	s_waitcnt lgkmcnt(0)
	v_add_f32_e32 v84, v84, v85
	ds_bpermute_b32 v85, v76, v84
	s_waitcnt lgkmcnt(0)
	v_add_f32_e32 v84, v84, v85
	v_fmamk_f32 v84, v84, 0x3a800000, v78
	v_mul_f32_e32 v85, 0x4f800000, v84
	v_cmp_gt_f32_e32 vcc, s21, v84
	s_nop 1
	v_cndmask_b32_e32 v84, v84, v85, vcc
	v_sqrt_f32_e32 v85, v84
	s_nop 0
	v_add_u32_e32 v86, -1, v85
	v_add_u32_e32 v87, 1, v85
	v_fma_f32 v88, -v86, v85, v84
	v_fma_f32 v89, -v87, v85, v84
	v_cmp_ge_f32_e64 s[0:1], 0, v88
	s_nop 1
	v_cndmask_b32_e64 v85, v85, v86, s[0:1]
	v_cmp_lt_f32_e64 s[0:1], 0, v89
	s_nop 1
	v_cndmask_b32_e64 v85, v85, v87, s[0:1]
	v_mul_f32_e32 v86, 0x37800000, v85
	v_cndmask_b32_e32 v85, v85, v86, vcc
	v_cmp_class_f32_e32 vcc, v84, v79
	s_nop 1
	v_cndmask_b32_e32 v86, v85, v84, vcc
	v_div_scale_f32 v87, s[0:1], v86, v86, 1.0
	v_rcp_f32_e32 v88, v87
	v_div_scale_f32 v89, vcc, 1.0, v86, 1.0
	v_lshl_add_u64 v[84:85], v[70:71], 0, s[22:23]
	v_fma_f32 v90, -v87, v88, 1.0
	v_fmac_f32_e32 v88, v90, v88
	v_mul_f32_e32 v90, v89, v88
	v_fma_f32 v91, -v87, v90, v89
	v_fmac_f32_e32 v90, v91, v88
	v_fma_f32 v87, -v87, v90, v89
	v_div_fmas_f32 v87, v87, v88, v90
	v_div_fixup_f32 v86, v87, v86, 1.0
	v_mul_f32_e32 v62, v62, v86
	v_mul_f32_e32 v63, v63, v86
	v_mul_f32_e32 v64, v64, v86
	v_mul_f32_e32 v65, v65, v86
	v_mul_f32_e32 v62, v180, v62
	v_mul_f32_e32 v63, v181, v63
	v_mul_f32_e32 v64, v182, v64
	v_mul_f32_e32 v65, v183, v65
	v_cvt_pk_bf16_f32 v62, v62, v63
	v_cvt_pk_bf16_f32 v63, v64, v65
	global_store_dwordx2 v[84:85], v[62:63], off
	v_mul_f32_e32 v58, v58, v86
	v_mul_f32_e32 v59, v59, v86
	v_mul_f32_e32 v60, v60, v86
	v_mul_f32_e32 v61, v61, v86
	v_mul_f32_e32 v54, v54, v86
	v_mul_f32_e32 v55, v55, v86
	v_mul_f32_e32 v56, v56, v86
	v_mul_f32_e32 v57, v57, v86
	v_mul_f32_e32 v50, v50, v86
	v_mul_f32_e32 v51, v51, v86
	v_mul_f32_e32 v52, v52, v86
	v_mul_f32_e32 v53, v53, v86
	s_andn2_b64 vcc, exec, s[16:17]
	v_mul_f32_e32 v58, v184, v58
	v_mul_f32_e32 v59, v185, v59
	v_mul_f32_e32 v60, v186, v60
	v_mul_f32_e32 v61, v187, v61
	v_cvt_pk_bf16_f32 v58, v58, v59
	v_cvt_pk_bf16_f32 v59, v60, v61
	global_store_dwordx2 v[84:85], v[58:59], off offset:512
	v_mul_f32_e32 v54, v54, v188
	v_mul_f32_e32 v55, v55, v189
	v_mul_f32_e32 v56, v56, v190
	v_mul_f32_e32 v57, v57, v191
	v_cvt_pk_bf16_f32 v54, v54, v55
	v_cvt_pk_bf16_f32 v55, v56, v57
	global_store_dwordx2 v[84:85], v[54:55], off offset:1024
	v_mul_f32_e32 v50, v50, v192
	v_mul_f32_e32 v51, v51, v193
	v_mul_f32_e32 v52, v52, v194
	v_mul_f32_e32 v53, v53, v195
	v_cvt_pk_bf16_f32 v50, v50, v51
	v_cvt_pk_bf16_f32 v51, v52, v53
	global_store_dwordx2 v[84:85], v[50:51], off offset:1536
	s_cbranch_vccz .LBB0_22
	s_andn2_b64 vcc, exec, s[14:15]
	s_cbranch_vccz .LBB0_23

.LBB0_22:
	v_mul_f32_e32 v50, v47, v47
	v_mul_f32_e32 v51, v49, v49
	v_fmac_f32_e32 v50, v46, v46
	v_fmac_f32_e32 v51, v48, v48
	v_add_f32_e32 v50, v50, v51
	v_mul_f32_e32 v51, v43, v43
	v_mul_f32_e32 v52, v45, v45
	v_fmac_f32_e32 v51, v42, v42
	v_fmac_f32_e32 v52, v44, v44
	v_add_f32_e32 v51, v51, v52
	v_add_f32_e32 v50, v51, v50
	v_mul_f32_e32 v51, v39, v39
	v_mul_f32_e32 v52, v41, v41
	v_fmac_f32_e32 v51, v38, v38
	v_fmac_f32_e32 v52, v40, v40
	v_add_f32_e32 v51, v51, v52
	v_add_f32_e32 v54, v51, v50
	v_mul_f32_e32 v55, v35, v35
	v_mul_f32_e32 v56, v37, v37
	v_fmac_f32_e32 v55, v34, v34
	v_fmac_f32_e32 v56, v36, v36
	v_add_f32_e32 v55, v55, v56
	v_add_f32_e32 v54, v55, v54
	ds_bpermute_b32 v55, v1, v54
	s_ashr_i32 s5, s4, 31
	s_lshl_b64 s[16:17], s[4:5], 11
	s_waitcnt lgkmcnt(0)
	v_add_f32_e32 v54, v54, v55
	ds_bpermute_b32 v55, v67, v54
	s_waitcnt lgkmcnt(0)
	v_add_f32_e32 v54, v54, v55
	ds_bpermute_b32 v55, v69, v54
	s_waitcnt lgkmcnt(0)
	v_add_f32_e32 v54, v54, v55
	ds_bpermute_b32 v55, v74, v54
	s_waitcnt lgkmcnt(0)
	v_add_f32_e32 v54, v54, v55
	ds_bpermute_b32 v55, v75, v54
	s_waitcnt lgkmcnt(0)
	v_add_f32_e32 v54, v54, v55
	ds_bpermute_b32 v55, v76, v54
	s_waitcnt lgkmcnt(0)
	v_add_f32_e32 v54, v54, v55
	v_fmamk_f32 v54, v54, 0x3a800000, v78
	v_mul_f32_e32 v55, 0x4f800000, v54
	v_cmp_gt_f32_e32 vcc, s21, v54
	s_nop 1
	v_cndmask_b32_e32 v54, v54, v55, vcc
	v_sqrt_f32_e32 v55, v54
	s_nop 0
	v_add_u32_e32 v56, -1, v55
	v_add_u32_e32 v57, 1, v55
	v_fma_f32 v58, -v56, v55, v54
	v_fma_f32 v59, -v57, v55, v54
	v_cmp_ge_f32_e64 s[0:1], 0, v58
	s_nop 1
	v_cndmask_b32_e64 v55, v55, v56, s[0:1]
	v_cmp_lt_f32_e64 s[0:1], 0, v59
	s_nop 1
	v_cndmask_b32_e64 v55, v55, v57, s[0:1]
	v_mul_f32_e32 v56, 0x37800000, v55
	v_cndmask_b32_e32 v55, v55, v56, vcc
	v_cmp_class_f32_e32 vcc, v54, v79
	s_nop 1
	v_cndmask_b32_e32 v56, v55, v54, vcc
	v_div_scale_f32 v57, s[0:1], v56, v56, 1.0
	v_rcp_f32_e32 v58, v57
	v_div_scale_f32 v59, vcc, 1.0, v56, 1.0
	v_lshl_add_u64 v[54:55], v[70:71], 0, s[16:17]
	v_fma_f32 v60, -v57, v58, 1.0
	v_fmac_f32_e32 v58, v60, v58
	v_mul_f32_e32 v60, v59, v58
	v_fma_f32 v61, -v57, v60, v59
	v_fmac_f32_e32 v60, v61, v58
	v_fma_f32 v57, -v57, v60, v59
	v_div_fmas_f32 v57, v57, v58, v60
	v_div_fixup_f32 v56, v57, v56, 1.0
	v_mul_f32_e32 v46, v46, v56
	v_mul_f32_e32 v47, v47, v56
	v_mul_f32_e32 v48, v48, v56
	v_mul_f32_e32 v49, v49, v56
	v_mul_f32_e32 v46, v180, v46
	v_mul_f32_e32 v47, v181, v47
	v_mul_f32_e32 v48, v182, v48
	v_mul_f32_e32 v49, v183, v49
	v_cvt_pk_bf16_f32 v46, v46, v47
	v_cvt_pk_bf16_f32 v47, v48, v49
	global_store_dwordx2 v[54:55], v[46:47], off
	v_mul_f32_e32 v42, v42, v56
	v_mul_f32_e32 v43, v43, v56
	v_mul_f32_e32 v44, v44, v56
	v_mul_f32_e32 v45, v45, v56
	v_mul_f32_e32 v38, v38, v56
	v_mul_f32_e32 v39, v39, v56
	v_mul_f32_e32 v40, v40, v56
	v_mul_f32_e32 v41, v41, v56
	v_mul_f32_e32 v34, v34, v56
	v_mul_f32_e32 v35, v35, v56
	v_mul_f32_e32 v36, v36, v56
	v_mul_f32_e32 v37, v37, v56
	v_mul_f32_e32 v42, v184, v42
	v_mul_f32_e32 v43, v185, v43
	v_mul_f32_e32 v44, v186, v44
	v_mul_f32_e32 v45, v187, v45
	v_cvt_pk_bf16_f32 v42, v42, v43
	v_cvt_pk_bf16_f32 v43, v44, v45
	global_store_dwordx2 v[54:55], v[42:43], off offset:512
	v_mul_f32_e32 v38, v38, v188
	v_mul_f32_e32 v39, v39, v189
	v_mul_f32_e32 v40, v40, v190
	v_mul_f32_e32 v41, v41, v191
	v_cvt_pk_bf16_f32 v38, v38, v39
	v_cvt_pk_bf16_f32 v39, v40, v41
	global_store_dwordx2 v[54:55], v[38:39], off offset:1024
	v_mul_f32_e32 v34, v34, v192
	v_mul_f32_e32 v35, v35, v193
	v_mul_f32_e32 v36, v36, v194
	v_mul_f32_e32 v37, v37, v195
	v_cvt_pk_bf16_f32 v34, v34, v35
	v_cvt_pk_bf16_f32 v35, v36, v37
	global_store_dwordx2 v[54:55], v[34:35], off offset:1536
	s_andn2_b64 vcc, exec, s[14:15]
	s_cbranch_vccnz .LBB0_21
.LBB0_23:
	v_mul_f32_e32 v34, v31, v31
	v_mul_f32_e32 v35, v33, v33
	v_fmac_f32_e32 v34, v30, v30
	v_fmac_f32_e32 v35, v32, v32
	v_add_f32_e32 v34, v34, v35
	v_mul_f32_e32 v35, v27, v27
	v_mul_f32_e32 v36, v29, v29
	v_fmac_f32_e32 v35, v26, v26
	v_fmac_f32_e32 v36, v28, v28
	v_add_f32_e32 v35, v35, v36
	v_add_f32_e32 v34, v35, v34
	v_mul_f32_e32 v35, v23, v23
	v_mul_f32_e32 v36, v25, v25
	v_fmac_f32_e32 v35, v22, v22
	v_fmac_f32_e32 v36, v24, v24
	v_add_f32_e32 v35, v35, v36
	v_add_f32_e32 v38, v35, v34
	v_mul_f32_e32 v39, v19, v19
	v_mul_f32_e32 v40, v21, v21
	v_fmac_f32_e32 v39, v18, v18
	v_fmac_f32_e32 v40, v20, v20
	v_add_f32_e32 v39, v39, v40
	v_add_f32_e32 v38, v39, v38
	ds_bpermute_b32 v39, v1, v38
	s_ashr_i32 s13, s12, 31
	s_lshl_b64 s[12:13], s[12:13], 11
	s_waitcnt lgkmcnt(0)
	v_add_f32_e32 v38, v38, v39
	ds_bpermute_b32 v39, v67, v38
	s_waitcnt lgkmcnt(0)
	v_add_f32_e32 v38, v38, v39
	ds_bpermute_b32 v39, v69, v38
	s_waitcnt lgkmcnt(0)
	v_add_f32_e32 v38, v38, v39
	ds_bpermute_b32 v39, v74, v38
	s_waitcnt lgkmcnt(0)
	v_add_f32_e32 v38, v38, v39
	ds_bpermute_b32 v39, v75, v38
	s_waitcnt lgkmcnt(0)
	v_add_f32_e32 v38, v38, v39
	ds_bpermute_b32 v39, v76, v38
	s_waitcnt lgkmcnt(0)
	v_add_f32_e32 v38, v38, v39
	v_fmamk_f32 v38, v38, 0x3a800000, v78
	v_mul_f32_e32 v39, 0x4f800000, v38
	v_cmp_gt_f32_e32 vcc, s21, v38
	s_nop 1
	v_cndmask_b32_e32 v38, v38, v39, vcc
	v_sqrt_f32_e32 v39, v38
	s_nop 0
	v_add_u32_e32 v40, -1, v39
	v_add_u32_e32 v41, 1, v39
	v_fma_f32 v42, -v40, v39, v38
	v_fma_f32 v43, -v41, v39, v38
	v_cmp_ge_f32_e64 s[0:1], 0, v42
	s_nop 1
	v_cndmask_b32_e64 v39, v39, v40, s[0:1]
	v_cmp_lt_f32_e64 s[0:1], 0, v43
	s_nop 1
	v_cndmask_b32_e64 v39, v39, v41, s[0:1]
	v_mul_f32_e32 v40, 0x37800000, v39
	v_cndmask_b32_e32 v39, v39, v40, vcc
	v_cmp_class_f32_e32 vcc, v38, v79
	s_nop 1
	v_cndmask_b32_e32 v40, v39, v38, vcc
	v_div_scale_f32 v41, s[0:1], v40, v40, 1.0
	v_rcp_f32_e32 v42, v41
	v_div_scale_f32 v43, vcc, 1.0, v40, 1.0
	v_lshl_add_u64 v[38:39], v[70:71], 0, s[12:13]
	v_fma_f32 v44, -v41, v42, 1.0
	v_fmac_f32_e32 v42, v44, v42
	v_mul_f32_e32 v44, v43, v42
	v_fma_f32 v45, -v41, v44, v43
	v_fmac_f32_e32 v44, v45, v42
	v_fma_f32 v41, -v41, v44, v43
	v_div_fmas_f32 v41, v41, v42, v44
	v_div_fixup_f32 v40, v41, v40, 1.0
	v_mul_f32_e32 v30, v30, v40
	v_mul_f32_e32 v31, v31, v40
	v_mul_f32_e32 v32, v32, v40
	v_mul_f32_e32 v33, v33, v40
	v_mul_f32_e32 v30, v180, v30
	v_mul_f32_e32 v31, v181, v31
	v_mul_f32_e32 v32, v182, v32
	v_mul_f32_e32 v33, v183, v33
	v_cvt_pk_bf16_f32 v30, v30, v31
	v_cvt_pk_bf16_f32 v31, v32, v33
	global_store_dwordx2 v[38:39], v[30:31], off
	v_mul_f32_e32 v26, v26, v40
	v_mul_f32_e32 v27, v27, v40
	v_mul_f32_e32 v28, v28, v40
	v_mul_f32_e32 v29, v29, v40
	v_mul_f32_e32 v22, v22, v40
	v_mul_f32_e32 v23, v23, v40
	v_mul_f32_e32 v24, v24, v40
	v_mul_f32_e32 v25, v25, v40
	v_mul_f32_e32 v18, v18, v40
	v_mul_f32_e32 v19, v19, v40
	v_mul_f32_e32 v20, v20, v40
	v_mul_f32_e32 v21, v21, v40
	v_mul_f32_e32 v26, v184, v26
	v_mul_f32_e32 v27, v185, v27
	v_mul_f32_e32 v28, v186, v28
	v_mul_f32_e32 v29, v187, v29
	v_cvt_pk_bf16_f32 v26, v26, v27
	v_cvt_pk_bf16_f32 v27, v28, v29
	global_store_dwordx2 v[38:39], v[26:27], off offset:512
	v_mul_f32_e32 v22, v22, v188
	v_mul_f32_e32 v23, v23, v189
	v_mul_f32_e32 v24, v24, v190
	v_mul_f32_e32 v25, v25, v191
	v_cvt_pk_bf16_f32 v22, v22, v23
	v_cvt_pk_bf16_f32 v23, v24, v25
	global_store_dwordx2 v[38:39], v[22:23], off offset:1024
	v_mul_f32_e32 v18, v18, v192
	v_mul_f32_e32 v19, v19, v193
	v_mul_f32_e32 v20, v20, v194
	v_mul_f32_e32 v21, v21, v195
	v_cvt_pk_bf16_f32 v18, v18, v19
	v_cvt_pk_bf16_f32 v19, v20, v21
	global_store_dwordx2 v[38:39], v[18:19], off offset:1536
	s_andn2_b64 vcc, exec, s[10:11]
	s_cbranch_vccnz .LBB0_12
.LBB0_24:
	v_mul_f32_e32 v18, v15, v15
	v_mul_f32_e32 v19, v17, v17
	v_fmac_f32_e32 v18, v14, v14
	v_fmac_f32_e32 v19, v16, v16
	v_add_f32_e32 v18, v18, v19
	v_mul_f32_e32 v19, v11, v11
	v_mul_f32_e32 v20, v13, v13
	v_fmac_f32_e32 v19, v10, v10
	v_fmac_f32_e32 v20, v12, v12
	v_add_f32_e32 v19, v19, v20
	v_add_f32_e32 v18, v19, v18
	v_mul_f32_e32 v19, v7, v7
	v_mul_f32_e32 v20, v9, v9
	v_fmac_f32_e32 v19, v6, v6
	v_fmac_f32_e32 v20, v8, v8
	v_add_f32_e32 v19, v19, v20
	v_add_f32_e32 v22, v19, v18
	v_mul_f32_e32 v23, v3, v3
	v_mul_f32_e32 v24, v5, v5
	v_fmac_f32_e32 v23, v2, v2
	v_fmac_f32_e32 v24, v4, v4
	v_add_f32_e32 v23, v23, v24
	v_add_f32_e32 v22, v23, v22
	ds_bpermute_b32 v23, v1, v22
	s_ashr_i32 s9, s8, 31
	s_lshl_b64 s[8:9], s[8:9], 11
	s_waitcnt lgkmcnt(0)
	v_add_f32_e32 v22, v22, v23
	ds_bpermute_b32 v23, v67, v22
	s_waitcnt lgkmcnt(0)
	v_add_f32_e32 v22, v22, v23
	ds_bpermute_b32 v23, v69, v22
	s_waitcnt lgkmcnt(0)
	v_add_f32_e32 v22, v22, v23
	ds_bpermute_b32 v23, v74, v22
	s_waitcnt lgkmcnt(0)
	v_add_f32_e32 v22, v22, v23
	ds_bpermute_b32 v23, v75, v22
	s_waitcnt lgkmcnt(0)
	v_add_f32_e32 v22, v22, v23
	ds_bpermute_b32 v23, v76, v22
	s_waitcnt lgkmcnt(0)
	v_add_f32_e32 v22, v22, v23
	v_fmamk_f32 v22, v22, 0x3a800000, v78
	v_mul_f32_e32 v23, 0x4f800000, v22
	v_cmp_gt_f32_e32 vcc, s21, v22
	s_nop 1
	v_cndmask_b32_e32 v22, v22, v23, vcc
	v_sqrt_f32_e32 v23, v22
	s_nop 0
	v_add_u32_e32 v24, -1, v23
	v_add_u32_e32 v25, 1, v23
	v_fma_f32 v26, -v24, v23, v22
	v_fma_f32 v27, -v25, v23, v22
	v_cmp_ge_f32_e64 s[0:1], 0, v26
	s_nop 1
	v_cndmask_b32_e64 v23, v23, v24, s[0:1]
	v_cmp_lt_f32_e64 s[0:1], 0, v27
	s_nop 1
	v_cndmask_b32_e64 v23, v23, v25, s[0:1]
	v_mul_f32_e32 v24, 0x37800000, v23
	v_cndmask_b32_e32 v23, v23, v24, vcc
	v_cmp_class_f32_e32 vcc, v22, v79
	s_nop 1
	v_cndmask_b32_e32 v24, v23, v22, vcc
	v_div_scale_f32 v25, s[0:1], v24, v24, 1.0
	v_rcp_f32_e32 v26, v25
	v_div_scale_f32 v27, vcc, 1.0, v24, 1.0
	v_lshl_add_u64 v[22:23], v[70:71], 0, s[8:9]
	v_fma_f32 v28, -v25, v26, 1.0
	v_fmac_f32_e32 v26, v28, v26
	v_mul_f32_e32 v28, v27, v26
	v_fma_f32 v29, -v25, v28, v27
	v_fmac_f32_e32 v28, v29, v26
	v_fma_f32 v25, -v25, v28, v27
	v_div_fmas_f32 v25, v25, v26, v28
	v_div_fixup_f32 v24, v25, v24, 1.0
	v_mul_f32_e32 v14, v14, v24
	v_mul_f32_e32 v15, v15, v24
	v_mul_f32_e32 v16, v16, v24
	v_mul_f32_e32 v17, v17, v24
	v_mul_f32_e32 v14, v180, v14
	v_mul_f32_e32 v15, v181, v15
	v_mul_f32_e32 v16, v182, v16
	v_mul_f32_e32 v17, v183, v17
	v_cvt_pk_bf16_f32 v14, v14, v15
	v_cvt_pk_bf16_f32 v15, v16, v17
	global_store_dwordx2 v[22:23], v[14:15], off
	v_mul_f32_e32 v10, v10, v24
	v_mul_f32_e32 v11, v11, v24
	v_mul_f32_e32 v12, v12, v24
	v_mul_f32_e32 v13, v13, v24
	v_mul_f32_e32 v6, v6, v24
	v_mul_f32_e32 v7, v7, v24
	v_mul_f32_e32 v8, v8, v24
	v_mul_f32_e32 v9, v9, v24
	v_mul_f32_e32 v2, v2, v24
	v_mul_f32_e32 v3, v3, v24
	v_mul_f32_e32 v4, v4, v24
	v_mul_f32_e32 v5, v5, v24
	v_mul_f32_e32 v10, v184, v10
	v_mul_f32_e32 v11, v185, v11
	v_mul_f32_e32 v12, v186, v12
	v_mul_f32_e32 v13, v187, v13
	v_cvt_pk_bf16_f32 v10, v10, v11
	v_cvt_pk_bf16_f32 v11, v12, v13
	global_store_dwordx2 v[22:23], v[10:11], off offset:512
	v_mul_f32_e32 v6, v6, v188
	v_mul_f32_e32 v7, v7, v189
	v_mul_f32_e32 v8, v8, v190
	v_mul_f32_e32 v9, v9, v191
	v_cvt_pk_bf16_f32 v6, v6, v7
	v_cvt_pk_bf16_f32 v7, v8, v9
	global_store_dwordx2 v[22:23], v[6:7], off offset:1024
	v_mul_f32_e32 v2, v2, v192
	v_mul_f32_e32 v3, v3, v193
	v_mul_f32_e32 v4, v4, v194
	v_mul_f32_e32 v5, v5, v195
	v_cvt_pk_bf16_f32 v2, v2, v3
	v_cvt_pk_bf16_f32 v3, v4, v5
	global_store_dwordx2 v[22:23], v[2:3], off offset:1536
	s_branch .LBB0_12
